# prologue: wave-major wave ids (gw = wave*G + bx) for the weight-transpose and x-conversion loops so every CU gets an equal share; MFMA f32 fold; pads keep 64B phase
# speedup vs baseline: 1.0177x; 1.0131x over previous
; #define LAS __attribute__((address_space(3)))
; #define TR(Wp, gn_, K_, N_, ldn_, dst_, ldk_, koff_) do { const int nblk_ = (N_) / 32, nit_ = ((K_) / 64) * nblk_; \
;         for (int it = gw; it < nit_; it += ngw) transpose_item((Wp), (gn_), (ldn_), nblk_, (bf16*)(dst_), (ldk_), (koff_), scr, it, lane); } while (0)
; __device__ __forceinline__ void prologue(const Params& p, LAS unsigned char* lds, int gw, int ngw, int wave, int lane) {
;     unsigned char* ws = p.ws;
;     LAS float* scr = (LAS float*)(lds + wave * 16384);
;     ...
;     const float* nog = nullptr;
;     TR(p.in[I_ABWIN], p.in[I_LNMIX], 1024, 1536, 1536, ws + W_WIN, 1024, 0);
.LBB0_5:
	s_or_b64 exec, exec, s[2:3]
	s_load_dwordx16 s[12:27], s[0:1], 0x80
	s_load_dwordx2 s[2:3], s[0:1], 0x120
	v_mov_b32_e32 v1, v216
	s_lshl_b32 s7, s52, 3
	v_readfirstlane_b32 s85, v1
	s_ashr_i32 s84, s85, 6
	s_waitcnt lgkmcnt(0)
	s_lshl_b32 s6, s2, 3
	s_lshl_b32 s2, s84, 14
	s_lshr_b32 s33, s6, 3
	s_mul_i32 s33, s33, s84
	s_add_i32 s33, s33, s52
	s_nop 0
	s_nop 0
	s_nop 0
	s_nop 0
	s_nop 0
	s_nop 0
	s_nop 0
	s_nop 0
	s_nop 0
	s_nop 0
	s_nop 0
	s_nop 0
	s_nop 0
	s_nop 0
	s_add_i32 s28, s2, 0
	v_and_b32_e32 v52, 63, v1
	s_cmpk_gt_i32 s33, 0x2ff
	s_cselect_b64 s[8:9], -1, 0
	s_cmpk_lt_i32 s33, 0x300
	v_lshrrev_b32_e32 v41, 5, v52
	v_lshlrev_b32_e32 v42, 2, v1
	v_lshrrev_b32_e32 v40, 3, v52
	v_lshlrev_b32_e32 v50, 3, v52
	s_cbranch_scc0 .LBB0_10
	v_and_b32_e32 v2, 56, v50
	s_cmp_lg_u64 s[38:39], 0
	v_lshrrev_b32_e32 v44, 3, v52
	v_lshlrev_b32_e32 v6, 1, v2
	v_mov_b32_e32 v7, 0
	s_cselect_b64 s[2:3], -1, 0
	v_lshrrev_b32_e32 v43, 5, v52
	v_and_b32_e32 v4, 0x7c, v42
	v_mul_u32_u24_e32 v5, 0x84, v2
	v_lshl_add_u64 v[2:3], s[94:95], 0, v[6:7]
	v_lshlrev_b32_e32 v6, 2, v44
	v_add_u32_e32 v8, s28, v4
	v_mul_u32_u24_e32 v9, 0x84, v43
	v_add3_u32 v45, s28, v5, v6
	v_mov_b32_e32 v5, v7
	v_cndmask_b32_e64 v6, 0, 1, s[2:3]
	v_lshl_add_u64 v[4:5], s[46:47], 0, v[4:5]
	s_lshl_b32 s29, s33, 5
	s_lshl_b32 s30, s6, 5
	s_movk_i32 s31, 0x1800
	v_add_u32_e32 v46, v8, v9
	v_cmp_ne_u32_e64 s[4:5], 1, v6
	s_mov_b32 s34, s33
	s_branch .LBB0_8

; __device__ __forceinline__ unsigned f2bf(float f) { return pg8::cvt_pk_bf16(f, 0.f) & 0xffffu; }
; __device__ __forceinline__ void prologue(const Params& p, LAS unsigned char* lds, int gw, int ngw, int wave, int lane) {
;     ...
;     {
;         const float* pw = p.in[I_ABPW]; const float* ps = p.in[I_ABPS]; const float* wo = p.in[I_ABWOUT] + (size_t)512 * 1024;
;         bf16* WT = (bf16*)(ws + W_WOUT);
;         const int gt = gw * 64 + lane, ngt = ngw * 64;
;         for (int o = gt; o < 128 * 1024; o += ngt) {
;             const int n = o & 1023, d = o >> 10;
;             float a[4] = {0.f, 0.f, 0.f, 0.f};
; #pragma unroll 4
;             for (int e = 0; e < 128; ++e) {
; #pragma unroll
;                 for (int g = 0; g < 4; ++g) a[g] += pw[((size_t)g * 128 + d) * 128 + e] * ps[g * 128 + e] * wo[((size_t)g * 128 + e) * 1024 + n]; }
; #pragma unroll
;             for (int g = 0; g < 4; ++g) WT[(size_t)n * 1024 + 512 + g * 128 + d] = (bf16)f2bf(a[g]); }
;     }
.LBB0_46:
	v_readlane_b32 s0, v240, 1
	v_lshl_or_b32 v54, s33, 6, v52
	s_mov_b32 s3, 0x20000
	v_readlane_b32 s1, v240, 2
	s_lshl_b32 s2, s0, 9
	v_cmp_gt_i32_e32 vcc, s3, v54
	s_mov_b64 exec, -1
	v_and_b32_e32 v1, 31, v52
	v_lshrrev_b32_e32 v14, 5, v52
	v_lshlrev_b32_e32 v10, 9, v1
	v_lshl_add_u32 v10, v14, 4, v10
	v_lshlrev_b32_e32 v11, 4, v14
	v_lshlrev_b32_e32 v12, 2, v1
	v_lshl_add_u32 v12, v14, 14, v12
	v_lshlrev_b32_e32 v13, 11, v1
	v_lshl_add_u32 v13, v14, 3, v13
	s_cmp_gt_u32 s84, 1
	s_cbranch_scc1 .Lfold_done
	v_readlane_b32 s28, v240, 16
	s_lshl_b32 s28, s28, 1
	s_add_u32 s28, s28, s84
	s_lshr_b32 s29, s2, 8

; __device__ __forceinline__ unsigned pk2(float lo, float hi) { return pg8::cvt_pk_bf16(lo, hi); }
; __device__ __forceinline__ void rms_row(const float* xrow, const float* g, bf16* orow, int lane) {
;     const f32x4* xr = (const f32x4*)xrow + lane; const f32x4* gr = (const f32x4*)g + lane;
;     f32x4 v[4]; float s = 0.f;
; #pragma unroll
;     for (int j = 0; j < 4; ++j) { v[j] = xr[64 * j]; s += (v[j].x * v[j].x + v[j].y * v[j].y) + (v[j].z * v[j].z + v[j].w * v[j].w); }
;     const float rs = rsqrtf(wave_sum(s) * (1.f / 1024.f) + EPS);
;     unsigned long long* o8 = (unsigned long long*)orow + lane;
; #pragma unroll
;     for (int j = 0; j < 4; ++j) { const f32x4 gg = gr[64 * j];
;         o8[64 * j] = (unsigned long long)pk2(v[j].x * rs * gg.x, v[j].y * rs * gg.y) | ((unsigned long long)pk2(v[j].z * rs * gg.z, v[j].w * rs * gg.w) << 32); }
; __device__ __forceinline__ void prologue(const Params& p, LAS unsigned char* lds, int gw, int ngw, int wave, int lane) {
;     ...
;     for (int m = gw; m < 2048; m += ngw) { const int l = m >> 10, r = m & 1023;
;         rms_row(p.in[I_MEMP] + (size_t)r * D, p.in[I_LNMEMKV] + l * D, (bf16*)(ws + W_MN) + (size_t)m * D, lane); }
.LBB0_70:
	s_or_b64 exec, exec, s[4:5]
	s_add_i32 s33, s84, s7
	s_nop 0
	s_nop 0
	s_nop 0
	s_nop 0
	s_nop 0
	s_nop 0
	s_nop 0
	s_nop 0
	s_nop 0
	s_nop 0
	s_nop 0
	s_nop 0
	s_nop 0
	s_nop 0
	s_nop 0
	s_cmpk_gt_i32 s33, 0x7ff
	s_cbranch_scc1 .LBB0_73
	v_mbcnt_hi_u32_b32 v2, -1, v217
	v_and_b32_e32 v1, 64, v2
	v_add_u32_e32 v3, 64, v1
	v_xor_b32_e32 v1, 1, v2
	v_cmp_lt_i32_e32 vcc, v1, v3
	v_xor_b32_e32 v4, 2, v2
	s_lshl_b32 s0, s62, 13
	v_cndmask_b32_e32 v1, v2, v1, vcc
	v_cmp_lt_i32_e32 vcc, v4, v3
	s_lshl_b32 s2, s84, 10
	s_add_i32 s4, s0, s2
	v_cndmask_b32_e32 v4, v2, v4, vcc
	v_lshlrev_b32_e32 v8, 2, v4
	v_xor_b32_e32 v4, 4, v2
	v_cmp_lt_i32_e32 vcc, v4, v3
	v_readlane_b32 s2, v240, 1
	v_readlane_b32 s3, v240, 2
	v_cndmask_b32_e32 v4, v2, v4, vcc
	v_lshlrev_b32_e32 v9, 2, v4
	v_xor_b32_e32 v4, 8, v2
	v_cmp_lt_i32_e32 vcc, v4, v3
	s_lshl_b32 s5, s2, 13
	s_ashr_i32 s0, s84, 31
	v_cndmask_b32_e32 v4, v2, v4, vcc
	v_lshlrev_b32_e32 v10, 2, v4
	v_xor_b32_e32 v4, 16, v2
	s_ashr_i32 s3, s7, 31
	v_cmp_lt_i32_e32 vcc, v4, v3
	s_add_u32 s2, s84, s7
	s_addc_u32 s3, s0, s3
	v_cndmask_b32_e32 v4, v2, v4, vcc
	v_lshlrev_b32_e32 v11, 2, v4
	v_xor_b32_e32 v4, 32, v2
	s_lshl_b64 s[2:3], s[2:3], 11
	v_cmp_lt_i32_e32 vcc, v4, v3
	v_mov_b32_e32 v7, 0
	s_add_u32 s2, s94, s2
	v_cndmask_b32_e32 v2, v2, v4, vcc
	v_lshlrev_b32_e32 v6, 4, v52
	v_mov_b32_e32 v51, v7
	s_addc_u32 s3, s95, s3
	v_lshlrev_b32_e32 v12, 2, v2
	v_lshl_add_u64 v[2:3], s[36:37], 0, v[6:7]
	v_lshl_add_u64 v[4:5], s[42:43], 0, v[6:7]
	v_lshl_add_u64 v[6:7], s[2:3], 0, v[50:51]
	s_mov_b64 s[2:3], 0x3300400
	s_ashr_i32 s7, s6, 31
	s_mov_b32 s1, 0
	v_lshlrev_b32_e32 v1, 2, v1
	v_lshl_add_u64 v[6:7], v[6:7], 0, s[2:3]
	s_lshl_b64 s[2:3], s[6:7], 11
	v_mov_b32_e32 v13, 0x358637bd
	s_mov_b32 s7, 0x800000
